# FFN-in GEMM K-loop LDS-DMA loads use scalar base + 32-bit per-lane offset (no 64-bit VALU address adds), on top of v61
# speedup vs baseline: 1.0084x; 1.0020x over previous
; #define PG8_STAGE(bufoff, gbase, voff) do { _Pragma("unroll") for (int _i = 0; _i < 2; ++_i) \
;         __builtin_amdgcn_global_load_lds((const unsigned*)((const char*)(gbase) + (voff)[_i]), (PG8_LAS unsigned*)(lds + (bufoff) + ldsw + _i * 8192), 16, 0, 0); } while (0)
; #define PG8_LDA(dst, b, h) do { _Pragma("unroll") for (int m = 0; m < 4; ++m) _Pragma("unroll") for (int k = 0; k < 2; ++k) dst[m][k] = *(const PG8_LAS bf16x8*)(lds + PG8_SA(b, h) + aoff + m * 2048 + k * 1024); } while (0)
; #define PG8_LDB(dst, b, h) do { _Pragma("unroll") for (int n = 0; n < 2; ++n) _Pragma("unroll") for (int k = 0; k < 2; ++k) dst[n][k] = *(const PG8_LAS bf16x8*)(lds + PG8_SB(b, h) + boff + n * 2048 + k * 1024); } while (0)
; #define PG8_MMA(ai, bj, At, Bt) do { __builtin_amdgcn_s_setprio(1); _Pragma("unroll") for (int m = 0; m < 4; ++m) _Pragma("unroll") for (int n = 0; n < 2; ++n) _Pragma("unroll") for (int k = 0; k < 2; ++k) \
;         acc[ai][bj][m][n] = __builtin_amdgcn_mfma_f32_16x16x32_bf16(Bt[n][k], At[m][k], acc[ai][bj][m][n], 0, 0, 0); __builtin_amdgcn_s_setprio(0); } while (0)
; #define PG8_WAIT_V(n) asm volatile("s_waitcnt vmcnt(" #n ")" ::: "memory")
; #define PG8_WAIT_L(n) asm volatile("s_waitcnt lgkmcnt(" #n ")" ::: "memory")
; template <class Epi, class Sched, bool ALIGN_EPI = false, bool SP2 = false>
; __device__ __forceinline__ void gemm_phase(PG8_LAS unsigned char* lds, const Gemm g, const Sched& S, const Epi& E, const int tid_in) {
;     ...
;             const bool last = (t == nt - 2);
;             const char* a1 = cA + (size_t)(t + 1) * kstep;
;             const char* a2 = last ? nA : cA + (size_t)(t + 2) * kstep; const char* b2 = last ? nB : cB + (size_t)(t + 2) * kstep;
;             const char* a3 = a2 + kstep; const char* b3 = b2 + kstep;
;             if (last && has_next) S.a_ready(nxt);
;             if constexpr (SP2) {
;             PG8_LDB(B0, 0, 0); PG8_LDB(B1, 0, 1); PG8_SCHED; PG8_LDA(At, 0, 0); PG8_STAGE(PG8_SA(1, 1), a1 + hstep, voffA);
;             PG8_WAIT_V(8); PG8_WAIT_L(0); PG8_BAR; PG8_MMA(0, 0, At, B0); PG8_MMA(0, 1, At, B1); PG8_BAR; PG8_SCHED;
;             PG8_LDA(At, 0, 1); PG8_STAGE(PG8_SB(0, 0), b2, voffB); PG8_STAGE(PG8_SB(0, 1), b2 + hstep, voffB); PG8_STAGE(PG8_SA(0, 0), a2, voffA);
;             PG8_WAIT_V(8); PG8_WAIT_L(0); PG8_BAR; PG8_MMA(1, 0, At, B0); PG8_MMA(1, 1, At, B1); PG8_BAR; PG8_SCHED;
.LBB0_307:
	s_add_u32 s20, s4, 0xfffc0080
	s_addc_u32 s21, s5, -1
	s_add_i32 s44, 0, 0x10000
	s_cmp_eq_u32 s43, 12
	s_cselect_b32 s23, s11, s21
	s_cselect_b32 s22, s39, s20
	s_cselect_b32 s21, s9, s42
	s_cselect_b32 s20, s40, s41
	s_add_i32 s46, 0, 0x14000
	v_add_u32_e32 v154, s44, v143
	v_add_u32_e32 v170, s46, v143
	ds_read_b128 v[138:141], v154
	ds_read_b128 v[146:149], v154 offset:1024
	ds_read_b128 v[150:153], v154 offset:2048
	ds_read_b128 v[154:157], v154 offset:3072
	ds_read_b128 v[158:161], v170
	ds_read_b128 v[162:165], v170 offset:1024
	ds_read_b128 v[166:169], v170 offset:2048
	ds_read_b128 v[170:173], v170 offset:3072
	s_add_i32 m0, s30, 0xc000
	ds_read_b128 v[174:177], v145
	ds_read_b128 v[178:181], v145 offset:1024
	ds_read_b128 v[182:185], v145 offset:2048
	ds_read_b128 v[186:189], v145 offset:3072
	ds_read_b128 v[200:203], v145 offset:4096
	ds_read_b128 v[204:207], v145 offset:5120
	ds_read_b128 v[208:211], v145 offset:6144
	ds_read_b128 v[212:215], v145 offset:7168
	global_load_lds_dwordx4 v134, s[4:5]
	s_add_i32 m0, s30, 0xe000
	s_nop 0
	global_load_lds_dwordx4 v136, s[4:5]
	s_waitcnt vmcnt(8)
	s_waitcnt lgkmcnt(0)
	s_barrier
	s_setprio 1
	s_waitcnt lgkmcnt(0)
	v_mfma_f32_16x16x32_bf16 v[124:127], v[138:141], v[174:177], v[124:127]
	v_mfma_f32_16x16x32_bf16 v[116:119], v[150:153], v[174:177], v[116:119]
	v_mfma_f32_16x16x32_bf16 v[108:111], v[138:141], v[182:185], v[108:111]
	v_mfma_f32_16x16x32_bf16 v[100:103], v[150:153], v[182:185], v[100:103]
	v_mfma_f32_16x16x32_bf16 v[92:95], v[138:141], v[200:203], v[92:95]
	v_mfma_f32_16x16x32_bf16 v[84:87], v[150:153], v[200:203], v[84:87]
	v_mfma_f32_16x16x32_bf16 v[76:79], v[138:141], v[208:211], v[76:79]
	v_mfma_f32_16x16x32_bf16 v[68:71], v[150:153], v[208:211], v[68:71]
	v_mfma_f32_16x16x32_bf16 v[124:127], v[146:149], v[178:181], v[124:127]
	v_mfma_f32_16x16x32_bf16 v[116:119], v[154:157], v[178:181], v[116:119]
	v_mfma_f32_16x16x32_bf16 v[108:111], v[146:149], v[186:189], v[108:111]
	v_mfma_f32_16x16x32_bf16 v[100:103], v[154:157], v[186:189], v[100:103]
	v_mfma_f32_16x16x32_bf16 v[92:95], v[146:149], v[204:207], v[92:95]
	v_mfma_f32_16x16x32_bf16 v[84:87], v[154:157], v[204:207], v[84:87]
	v_mfma_f32_16x16x32_bf16 v[76:79], v[146:149], v[212:215], v[76:79]
	v_mfma_f32_16x16x32_bf16 v[68:71], v[154:157], v[212:215], v[68:71]
	s_setprio 0
	s_setprio 1
	v_mfma_f32_16x16x32_bf16 v[120:123], v[158:161], v[174:177], v[120:123]
	v_mfma_f32_16x16x32_bf16 v[112:115], v[166:169], v[174:177], v[112:115]
	v_mfma_f32_16x16x32_bf16 v[104:107], v[158:161], v[182:185], v[104:107]
	v_mfma_f32_16x16x32_bf16 v[96:99], v[166:169], v[182:185], v[96:99]
	v_mfma_f32_16x16x32_bf16 v[88:91], v[158:161], v[200:203], v[88:91]
	v_mfma_f32_16x16x32_bf16 v[80:83], v[166:169], v[200:203], v[80:83]
	v_mfma_f32_16x16x32_bf16 v[72:75], v[158:161], v[208:211], v[72:75]
	v_mfma_f32_16x16x32_bf16 v[64:67], v[166:169], v[208:211], v[64:67]
	v_mfma_f32_16x16x32_bf16 v[120:123], v[162:165], v[178:181], v[120:123]
	v_mfma_f32_16x16x32_bf16 v[112:115], v[170:173], v[178:181], v[112:115]
	v_mfma_f32_16x16x32_bf16 v[104:107], v[162:165], v[186:189], v[104:107]
	v_mfma_f32_16x16x32_bf16 v[96:99], v[170:173], v[186:189], v[96:99]
	v_mfma_f32_16x16x32_bf16 v[88:91], v[162:165], v[204:207], v[88:91]
	v_mfma_f32_16x16x32_bf16 v[80:83], v[170:173], v[204:207], v[80:83]
	v_mfma_f32_16x16x32_bf16 v[72:75], v[162:165], v[212:215], v[72:75]
	v_mfma_f32_16x16x32_bf16 v[64:67], v[170:173], v[212:215], v[64:67]
	s_setprio 0
	s_barrier
	s_add_i32 s44, s44, s27
	s_mov_b32 m0, s44
	ds_read_b128 v[174:177], v145 offset:16384
	ds_read_b128 v[178:181], v145 offset:17408
	ds_read_b128 v[182:185], v145 offset:18432
	ds_read_b128 v[186:189], v145 offset:19456
	ds_read_b128 v[200:203], v145 offset:20480
	ds_read_b128 v[204:207], v145 offset:21504
	ds_read_b128 v[208:211], v145 offset:22528
	ds_read_b128 v[212:215], v145 offset:23552
	global_load_lds_dwordx4 v192, s[20:21]
	s_add_i32 m0, s44, 0x2000
	s_add_u32 s44, s20, 0x40000
	s_addc_u32 s45, s21, 0
	s_add_i32 s46, s46, s27
	global_load_lds_dwordx4 v128, s[20:21]
	s_mov_b32 m0, s46
	s_nop 0
	global_load_lds_dwordx4 v192, s[44:45]
	s_add_i32 m0, s46, 0x2000
	s_nop 0
	global_load_lds_dwordx4 v128, s[44:45]
	s_mov_b32 m0, s30
	s_nop 0
	global_load_lds_dwordx4 v132, s[22:23]
	s_mov_b32 m0, s31
	s_nop 0
	global_load_lds_dwordx4 v130, s[22:23]
	s_waitcnt vmcnt(8)
	s_waitcnt lgkmcnt(0)
	s_barrier
	s_setprio 1
	s_waitcnt lgkmcnt(0)
	v_mfma_f32_16x16x32_bf16 v[60:63], v[138:141], v[174:177], v[60:63]
	v_mfma_f32_16x16x32_bf16 v[52:55], v[150:153], v[174:177], v[52:55]
	v_mfma_f32_16x16x32_bf16 v[44:47], v[138:141], v[182:185], v[44:47]
	v_mfma_f32_16x16x32_bf16 v[36:39], v[150:153], v[182:185], v[36:39]
	v_mfma_f32_16x16x32_bf16 v[28:31], v[138:141], v[200:203], v[28:31]
	v_mfma_f32_16x16x32_bf16 v[20:23], v[150:153], v[200:203], v[20:23]
	v_mfma_f32_16x16x32_bf16 v[12:15], v[138:141], v[208:211], v[12:15]
	v_mfma_f32_16x16x32_bf16 v[4:7], v[150:153], v[208:211], v[4:7]
	v_mfma_f32_16x16x32_bf16 v[60:63], v[146:149], v[178:181], v[60:63]
	v_mfma_f32_16x16x32_bf16 v[52:55], v[154:157], v[178:181], v[52:55]
	v_mfma_f32_16x16x32_bf16 v[44:47], v[146:149], v[186:189], v[44:47]
	v_mfma_f32_16x16x32_bf16 v[36:39], v[154:157], v[186:189], v[36:39]
	v_mfma_f32_16x16x32_bf16 v[28:31], v[146:149], v[204:207], v[28:31]
	v_mfma_f32_16x16x32_bf16 v[20:23], v[154:157], v[204:207], v[20:23]
	v_mfma_f32_16x16x32_bf16 v[12:15], v[146:149], v[212:215], v[12:15]
	v_mfma_f32_16x16x32_bf16 v[4:7], v[154:157], v[212:215], v[4:7]
	s_setprio 0
	s_setprio 1
	v_mfma_f32_16x16x32_bf16 v[56:59], v[158:161], v[174:177], v[56:59]
	v_mfma_f32_16x16x32_bf16 v[48:51], v[166:169], v[174:177], v[48:51]
	v_mfma_f32_16x16x32_bf16 v[40:43], v[158:161], v[182:185], v[40:43]
	v_mfma_f32_16x16x32_bf16 v[32:35], v[166:169], v[182:185], v[32:35]
	v_mfma_f32_16x16x32_bf16 v[24:27], v[158:161], v[200:203], v[24:27]
	v_mfma_f32_16x16x32_bf16 v[16:19], v[166:169], v[200:203], v[16:19]
	v_mfma_f32_16x16x32_bf16 v[8:11], v[158:161], v[208:211], v[8:11]
	v_mfma_f32_16x16x32_bf16 v[0:3], v[166:169], v[208:211], v[0:3]
	v_mfma_f32_16x16x32_bf16 v[56:59], v[162:165], v[178:181], v[56:59]
	v_mfma_f32_16x16x32_bf16 v[48:51], v[170:173], v[178:181], v[48:51]
	v_mfma_f32_16x16x32_bf16 v[40:43], v[162:165], v[186:189], v[40:43]
	v_mfma_f32_16x16x32_bf16 v[32:35], v[170:173], v[186:189], v[32:35]
	v_mfma_f32_16x16x32_bf16 v[24:27], v[162:165], v[204:207], v[24:27]
	v_mfma_f32_16x16x32_bf16 v[16:19], v[170:173], v[204:207], v[16:19]
	v_mfma_f32_16x16x32_bf16 v[8:11], v[162:165], v[212:215], v[8:11]
	v_mfma_f32_16x16x32_bf16 v[0:3], v[170:173], v[212:215], v[0:3]
	s_setprio 0
	s_barrier
; #define PG8_STAGE(bufoff, gbase, voff) do { _Pragma("unroll") for (int _i = 0; _i < 2; ++_i) \
;         __builtin_amdgcn_global_load_lds((const unsigned*)((const char*)(gbase) + (voff)[_i]), (PG8_LAS unsigned*)(lds + (bufoff) + ldsw + _i * 8192), 16, 0, 0); } while (0)
; #define PG8_LDA(dst, b, h) do { _Pragma("unroll") for (int m = 0; m < 4; ++m) _Pragma("unroll") for (int k = 0; k < 2; ++k) dst[m][k] = *(const PG8_LAS bf16x8*)(lds + PG8_SA(b, h) + aoff + m * 2048 + k * 1024); } while (0)
; #define PG8_WAIT_V(n) asm volatile("s_waitcnt vmcnt(" #n ")" ::: "memory")
; #define PG8_WAIT_L(n) asm volatile("s_waitcnt lgkmcnt(" #n ")" ::: "memory")
; #define PG8_BAR __builtin_amdgcn_s_barrier()
; template <class Epi, class Sched, bool ALIGN_EPI = false, bool SP2 = false>
; __device__ __forceinline__ void gemm_phase(PG8_LAS unsigned char* lds, const Gemm g, const Sched& S, const Epi& E, const int tid_in) {
;     ...
;         for (int t = 0; t < nt; t += 2) {
;             const bool last = (t == nt - 2);
;             const char* a1 = cA + (size_t)(t + 1) * kstep;
;             const char* a2 = last ? nA : cA + (size_t)(t + 2) * kstep; const char* b2 = last ? nB : cB + (size_t)(t + 2) * kstep;
;             const char* a3 = a2 + kstep; const char* b3 = b2 + kstep;
;             if (last && has_next) S.a_ready(nxt);
;             if constexpr (SP2) {
;             PG8_LDB(B0, 0, 0); PG8_LDB(B1, 0, 1); PG8_SCHED; PG8_LDA(At, 0, 0); PG8_STAGE(PG8_SA(1, 1), a1 + hstep, voffA);
;             PG8_WAIT_V(8); PG8_WAIT_L(0); PG8_BAR; PG8_MMA(0, 0, At, B0); PG8_MMA(0, 1, At, B1); PG8_BAR; PG8_SCHED;
;             PG8_LDA(At, 0, 1); PG8_STAGE(PG8_SB(0, 0), b2, voffB); PG8_STAGE(PG8_SB(0, 1), b2 + hstep, voffB); PG8_STAGE(PG8_SA(0, 0), a2, voffA);
;             PG8_WAIT_V(8); PG8_WAIT_L(0); PG8_BAR; PG8_MMA(1, 0, At, B0); PG8_MMA(1, 1, At, B1); PG8_BAR; PG8_SCHED;
;             PG8_LDB(B0, 1, 0); PG8_LDB(B1, 1, 1); PG8_SCHED; PG8_LDA(At, 1, 0); PG8_STAGE(PG8_SA(0, 1), a2 + hstep, voffA);
;             PG8_WAIT_V(8); PG8_WAIT_L(0); PG8_BAR; PG8_MMA(0, 0, At, B0); PG8_MMA(0, 1, At, B1); PG8_BAR; PG8_SCHED;
;             PG8_LDA(At, 1, 1); PG8_STAGE(PG8_SB(1, 0), b3, voffB); PG8_STAGE(PG8_SB(1, 1), b3 + hstep, voffB); PG8_STAGE(PG8_SA(1, 0), a3, voffA);
;             PG8_WAIT_V(8); PG8_WAIT_L(0); PG8_BAR; PG8_MMA(1, 0, At, B0); PG8_MMA(1, 1, At, B1); PG8_BAR; PG8_SCHED;
	s_add_i32 s44, 0, 0x18000
	s_add_i32 s45, 0, 0x1c000
	v_add_u32_e32 v154, s44, v143
	v_add_u32_e32 v170, s45, v143
	ds_read_b128 v[138:141], v154
	ds_read_b128 v[146:149], v154 offset:1024
	ds_read_b128 v[150:153], v154 offset:2048
	ds_read_b128 v[154:157], v154 offset:3072
	ds_read_b128 v[158:161], v170
	ds_read_b128 v[162:165], v170 offset:1024
	ds_read_b128 v[166:169], v170 offset:2048
	ds_read_b128 v[170:173], v170 offset:3072
	s_add_u32 s22, s22, 0x40000
	s_addc_u32 s23, s23, 0
	s_mov_b32 m0, s34
	ds_read_b128 v[174:177], v145 offset:32768
	ds_read_b128 v[178:181], v145 offset:33792
	ds_read_b128 v[182:185], v145 offset:34816
	ds_read_b128 v[186:189], v145 offset:35840
	ds_read_b128 v[200:203], v145 offset:36864
	ds_read_b128 v[204:207], v145 offset:37888
	ds_read_b128 v[208:211], v145 offset:38912
	ds_read_b128 v[212:215], v145 offset:39936
	global_load_lds_dwordx4 v132, s[22:23]
	s_mov_b32 m0, s35
	s_nop 0
	global_load_lds_dwordx4 v130, s[22:23]
	s_waitcnt vmcnt(8)
	s_waitcnt lgkmcnt(0)
	s_barrier
	s_setprio 1
	s_waitcnt lgkmcnt(0)
	v_mfma_f32_16x16x32_bf16 v[124:127], v[138:141], v[174:177], v[124:127]
	v_mfma_f32_16x16x32_bf16 v[116:119], v[150:153], v[174:177], v[116:119]
	v_mfma_f32_16x16x32_bf16 v[108:111], v[138:141], v[182:185], v[108:111]
	v_mfma_f32_16x16x32_bf16 v[100:103], v[150:153], v[182:185], v[100:103]
	v_mfma_f32_16x16x32_bf16 v[92:95], v[138:141], v[200:203], v[92:95]
	v_mfma_f32_16x16x32_bf16 v[84:87], v[150:153], v[200:203], v[84:87]
	v_mfma_f32_16x16x32_bf16 v[76:79], v[138:141], v[208:211], v[76:79]
	v_mfma_f32_16x16x32_bf16 v[68:71], v[150:153], v[208:211], v[68:71]
	v_mfma_f32_16x16x32_bf16 v[124:127], v[146:149], v[178:181], v[124:127]
	v_mfma_f32_16x16x32_bf16 v[116:119], v[154:157], v[178:181], v[116:119]
	v_mfma_f32_16x16x32_bf16 v[108:111], v[146:149], v[186:189], v[108:111]
	v_mfma_f32_16x16x32_bf16 v[100:103], v[154:157], v[186:189], v[100:103]
	v_mfma_f32_16x16x32_bf16 v[92:95], v[146:149], v[204:207], v[92:95]
	v_mfma_f32_16x16x32_bf16 v[84:87], v[154:157], v[204:207], v[84:87]
	v_mfma_f32_16x16x32_bf16 v[76:79], v[146:149], v[212:215], v[76:79]
	v_mfma_f32_16x16x32_bf16 v[68:71], v[154:157], v[212:215], v[68:71]
	s_setprio 0
	s_setprio 1
	v_mfma_f32_16x16x32_bf16 v[120:123], v[158:161], v[174:177], v[120:123]
	v_mfma_f32_16x16x32_bf16 v[112:115], v[166:169], v[174:177], v[112:115]
	v_mfma_f32_16x16x32_bf16 v[104:107], v[158:161], v[182:185], v[104:107]
	v_mfma_f32_16x16x32_bf16 v[96:99], v[166:169], v[182:185], v[96:99]
	v_mfma_f32_16x16x32_bf16 v[88:91], v[158:161], v[200:203], v[88:91]
	v_mfma_f32_16x16x32_bf16 v[80:83], v[166:169], v[200:203], v[80:83]
	v_mfma_f32_16x16x32_bf16 v[72:75], v[158:161], v[208:211], v[72:75]
	v_mfma_f32_16x16x32_bf16 v[64:67], v[166:169], v[208:211], v[64:67]
	v_mfma_f32_16x16x32_bf16 v[120:123], v[162:165], v[178:181], v[120:123]
	v_mfma_f32_16x16x32_bf16 v[112:115], v[170:173], v[178:181], v[112:115]
	v_mfma_f32_16x16x32_bf16 v[104:107], v[162:165], v[186:189], v[104:107]
	v_mfma_f32_16x16x32_bf16 v[96:99], v[170:173], v[186:189], v[96:99]
	v_mfma_f32_16x16x32_bf16 v[88:91], v[162:165], v[204:207], v[88:91]
	v_mfma_f32_16x16x32_bf16 v[80:83], v[170:173], v[204:207], v[80:83]
	v_mfma_f32_16x16x32_bf16 v[72:75], v[162:165], v[212:215], v[72:75]
	v_mfma_f32_16x16x32_bf16 v[64:67], v[170:173], v[212:215], v[64:67]
	s_setprio 0
	s_barrier
	s_sub_u32 s22, s22, 0x3ff80
	s_subb_u32 s23, s23, 0
	s_add_u32 s20, s20, 0x80
	s_addc_u32 s21, s21, 0
	s_add_i32 s46, s44, s27
	s_mov_b32 m0, s46
	ds_read_b128 v[174:177], v145 offset:49152
	ds_read_b128 v[178:181], v145 offset:50176
	ds_read_b128 v[182:185], v145 offset:51200
	ds_read_b128 v[186:189], v145 offset:52224
	ds_read_b128 v[200:203], v145 offset:53248
	ds_read_b128 v[204:207], v145 offset:54272
	ds_read_b128 v[208:211], v145 offset:55296
	ds_read_b128 v[212:215], v145 offset:56320
	global_load_lds_dwordx4 v192, s[20:21]
	s_add_i32 m0, s46, 0x2000
	s_add_i32 s46, s45, s27
	global_load_lds_dwordx4 v128, s[20:21]
	s_add_u32 s20, s20, 0x40000
	s_addc_u32 s21, s21, 0
	s_mov_b32 m0, s46
	s_nop 0
	global_load_lds_dwordx4 v192, s[20:21]
	s_add_i32 m0, s46, 0x2000
	s_nop 0
	global_load_lds_dwordx4 v128, s[20:21]
	s_mov_b32 m0, s36
	s_nop 0
	global_load_lds_dwordx4 v132, s[22:23]
	s_mov_b32 m0, s37
	s_nop 0
	global_load_lds_dwordx4 v130, s[22:23]
	s_waitcnt vmcnt(8)
	s_waitcnt lgkmcnt(0)
	s_barrier
	s_setprio 1
	s_waitcnt lgkmcnt(0)
	v_mfma_f32_16x16x32_bf16 v[60:63], v[138:141], v[174:177], v[60:63]
	v_mfma_f32_16x16x32_bf16 v[52:55], v[150:153], v[174:177], v[52:55]
	v_mfma_f32_16x16x32_bf16 v[44:47], v[138:141], v[182:185], v[44:47]
	v_mfma_f32_16x16x32_bf16 v[36:39], v[150:153], v[182:185], v[36:39]
	v_mfma_f32_16x16x32_bf16 v[28:31], v[138:141], v[200:203], v[28:31]
	v_mfma_f32_16x16x32_bf16 v[20:23], v[150:153], v[200:203], v[20:23]
	v_mfma_f32_16x16x32_bf16 v[12:15], v[138:141], v[208:211], v[12:15]
	v_mfma_f32_16x16x32_bf16 v[4:7], v[150:153], v[208:211], v[4:7]
	v_mfma_f32_16x16x32_bf16 v[60:63], v[146:149], v[178:181], v[60:63]
	v_mfma_f32_16x16x32_bf16 v[52:55], v[154:157], v[178:181], v[52:55]
	v_mfma_f32_16x16x32_bf16 v[44:47], v[146:149], v[186:189], v[44:47]
	v_mfma_f32_16x16x32_bf16 v[36:39], v[154:157], v[186:189], v[36:39]
	v_mfma_f32_16x16x32_bf16 v[28:31], v[146:149], v[204:207], v[28:31]
	v_mfma_f32_16x16x32_bf16 v[20:23], v[154:157], v[204:207], v[20:23]
	v_mfma_f32_16x16x32_bf16 v[12:15], v[146:149], v[212:215], v[12:15]
	v_mfma_f32_16x16x32_bf16 v[4:7], v[154:157], v[212:215], v[4:7]
	s_setprio 0
	s_setprio 1
	v_mfma_f32_16x16x32_bf16 v[56:59], v[158:161], v[174:177], v[56:59]
	v_mfma_f32_16x16x32_bf16 v[48:51], v[166:169], v[174:177], v[48:51]
	v_mfma_f32_16x16x32_bf16 v[40:43], v[158:161], v[182:185], v[40:43]
	v_mfma_f32_16x16x32_bf16 v[32:35], v[166:169], v[182:185], v[32:35]
	v_mfma_f32_16x16x32_bf16 v[24:27], v[158:161], v[200:203], v[24:27]
	v_mfma_f32_16x16x32_bf16 v[16:19], v[166:169], v[200:203], v[16:19]
	v_mfma_f32_16x16x32_bf16 v[8:11], v[158:161], v[208:211], v[8:11]
	v_mfma_f32_16x16x32_bf16 v[0:3], v[166:169], v[208:211], v[0:3]
	v_mfma_f32_16x16x32_bf16 v[56:59], v[162:165], v[178:181], v[56:59]
	v_mfma_f32_16x16x32_bf16 v[48:51], v[170:173], v[178:181], v[48:51]
	v_mfma_f32_16x16x32_bf16 v[40:43], v[162:165], v[186:189], v[40:43]
	v_mfma_f32_16x16x32_bf16 v[32:35], v[170:173], v[186:189], v[32:35]
	v_mfma_f32_16x16x32_bf16 v[24:27], v[162:165], v[204:207], v[24:27]
	v_mfma_f32_16x16x32_bf16 v[16:19], v[170:173], v[204:207], v[16:19]
	v_mfma_f32_16x16x32_bf16 v[8:11], v[162:165], v[212:215], v[8:11]
	v_mfma_f32_16x16x32_bf16 v[0:3], v[170:173], v[212:215], v[0:3]
	s_setprio 0
	s_barrier
	s_add_i32 s43, s43, 2
	s_add_u32 s4, s4, 0x100
	s_addc_u32 s5, s5, 0
	s_add_u32 s41, s41, 0x100
	s_addc_u32 s42, s42, 0
	s_cmp_gt_u32 s43, 13
	s_cbranch_scc0 .LBB0_307
	s_and_b64 vcc, exec, s[18:19]
	s_cbranch_vccz .LBB0_310
	s_barrier
